# static younger-half priority: every per-phase s_setprio flip in the GEMM k-loops deleted, one s_setprio 1 for waves 0-3 at kernel entry
# speedup vs baseline: 1.0060x; 1.0056x over previous
; #define LAS __attribute__((address_space(3)))
; __global__ void __launch_bounds__(NTHREADS, 2) fwd_megakernel(Args a) {
;     extern __shared__ __attribute__((aligned(16))) unsigned char lds_raw[];
;     LAS unsigned char* lds = (LAS unsigned char*)lds_raw;
;     cg::grid_group grid = cg::this_grid();
;     const int tid = threadIdx.x, lane = tid & 63, wave = __builtin_amdgcn_readfirstlane(tid >> 6);
_Z14fwd_megakernel4Args:
	s_load_dwordx2 s[66:67], s[0:1], 0xd8
	s_load_dword s54, s[0:1], 0xe0
	s_add_u32 s34, s0, 0xd8
	v_and_b32_e32 v160, 0x3ff, v0
	s_addc_u32 s35, s1, 0
	v_readfirstlane_b32 s3, v160
	v_cmp_eq_u32_e64 s[4:5], 0, v160
	s_nop 0
	v_writelane_b32 v243, s3, 0
	s_nop 1
	s_lshr_b32 s98, s3, 6
	s_cmp_lt_u32 s98, 4
	s_cbranch_scc0 .Lprio_done
	s_setprio 1
